# LRU gate epilogue: IEEE sqrt expansion -> v_sqrt_f32
# baseline (speedup 1.0000x reference)
.LBB0_373:
	s_or_b64 exec, exec, s[4:5]
	s_mov_b32 s4, 0xf800000
	v_sqrt_f32_e32 v81, v81
	s_nop 0

.LBB0_376:
	v_add_u32_e32 v95, s49, v139
	v_ashrrev_i32_e32 v74, 5, v95
	v_add_u32_e32 v84, s48, v74
	s_movk_i32 s4, 0x4080
	v_cmp_gt_i32_e32 vcc, s4, v84
	s_and_saveexec_b64 s[10:11], vcc
	s_cbranch_execz .LBB0_402
	v_ashrrev_i32_e32 v85, 31, v84
	v_lshlrev_b64 v[76:77], 10, v[84:85]
	v_lshl_add_u64 v[76:77], v[140:141], 0, v[76:77]
	global_load_dwordx2 v[82:83], v[76:77], off
	v_mad_u64_u32 v[74:75], s[4:5], v74, s33, v[138:139]
	ds_read_b128 v[78:81], v74
	ds_read_b128 v[74:77], v74 offset:512
	s_movk_i32 s4, 0x3fff
	v_cmp_lt_i32_e32 vcc, s4, v84
	v_and_b32_e32 v96, 0xfff, v84
	s_waitcnt vmcnt(2) lgkmcnt(1)
	v_add_f32_e32 v78, v2, v78
	v_mul_f32_e32 v78, 0xbfb8aa3b, v78
	v_exp_f32_e32 v78, v78
	s_nop 0
	v_add_f32_e32 v78, 1.0, v78
	v_cmp_ne_u32_e64 s[4:5], 0, v96
	s_or_b64 s[24:25], vcc, s[4:5]
	v_mov_b32_e32 v96, 1.0
	v_rcp_f32_e32 v78, v78
	s_nop 0
	v_mul_f32_e32 v78, 0xc1000000, v78
	v_mul_f32_e32 v78, v146, v78
	s_and_saveexec_b64 s[26:27], s[24:25]
	s_cbranch_execz .LBB0_383
	v_add_f32_e32 v97, v78, v78
	s_mov_b32 s4, 0xbdcccccd
	v_cmp_nlt_f32_e32 vcc, s4, v97
	s_and_saveexec_b64 s[4:5], vcc
	s_xor_b64 s[4:5], exec, s[4:5]
	v_mul_f32_e32 v96, 0x3fb8aa3b, v97
	v_exp_f32_e32 v96, v96
	s_nop 0
	v_sub_f32_e32 v96, 1.0, v96
	s_andn2_saveexec_b64 s[4:5], s[4:5]
	v_fmamk_f32 v96, v97, 0x3d2aaaab, v171
	v_fma_f32 v96, v97, v96, 0.5
	v_fma_f32 v96, v97, v96, 1.0
	v_mul_f32_e64 v96, v97, -v96
	s_or_b64 exec, exec, s[4:5]
	s_mov_b32 s4, 0xf800000
	v_sqrt_f32_e32 v96, v96
	s_nop 0
.LBB0_383:
	s_or_b64 exec, exec, s[26:27]
	v_add_f32_e32 v79, v3, v79
	v_mul_f32_e32 v79, 0xbfb8aa3b, v79
	v_exp_f32_e32 v79, v79
	v_lshlrev_b64 v[84:85], 9, v[84:85]
	v_mov_b32_e32 v97, 1.0
	v_add_f32_e32 v79, 1.0, v79
	v_rcp_f32_e32 v79, v79
	s_nop 0
	v_mul_f32_e32 v79, 0xc1000000, v79
	v_mul_f32_e32 v79, v147, v79
	s_and_saveexec_b64 s[26:27], s[24:25]
	s_cbranch_execz .LBB0_389
	v_add_f32_e32 v99, v79, v79
	s_mov_b32 s4, 0xbdcccccd
	v_cmp_nlt_f32_e32 vcc, s4, v99
	s_and_saveexec_b64 s[4:5], vcc
	s_xor_b64 s[4:5], exec, s[4:5]
	v_mul_f32_e32 v97, 0x3fb8aa3b, v99
	v_exp_f32_e32 v97, v97
	s_nop 0
	v_sub_f32_e32 v97, 1.0, v97
	s_andn2_saveexec_b64 s[4:5], s[4:5]
	v_fmamk_f32 v97, v99, 0x3d2aaaab, v171
	v_fma_f32 v97, v99, v97, 0.5
	v_fma_f32 v97, v99, v97, 1.0
	v_mul_f32_e64 v97, v99, -v97
	s_or_b64 exec, exec, s[4:5]
	s_mov_b32 s4, 0xf800000
	v_sqrt_f32_e32 v97, v97
	s_nop 0
.LBB0_389:
	s_or_b64 exec, exec, s[26:27]
	v_add_f32_e32 v80, v4, v80
	v_mul_f32_e32 v80, 0xbfb8aa3b, v80
	v_exp_f32_e32 v80, v80
	v_mov_b32_e32 v99, 1.0
	v_add_f32_e32 v80, 1.0, v80
	v_rcp_f32_e32 v80, v80
	s_nop 0
	v_mul_f32_e32 v80, 0xc1000000, v80
	v_mul_f32_e32 v80, v148, v80
	s_and_saveexec_b64 s[26:27], s[24:25]
	s_cbranch_execz .LBB0_395
	v_add_f32_e32 v100, v80, v80
	s_mov_b32 s4, 0xbdcccccd
	v_cmp_nlt_f32_e32 vcc, s4, v100
	s_and_saveexec_b64 s[4:5], vcc
	s_xor_b64 s[4:5], exec, s[4:5]
	v_mul_f32_e32 v99, 0x3fb8aa3b, v100
	v_exp_f32_e32 v99, v99
	s_nop 0
	v_sub_f32_e32 v99, 1.0, v99
	s_andn2_saveexec_b64 s[4:5], s[4:5]
	v_fmamk_f32 v99, v100, 0x3d2aaaab, v171
	v_fma_f32 v99, v100, v99, 0.5
	v_fma_f32 v99, v100, v99, 1.0
	v_mul_f32_e64 v99, v100, -v99
	s_or_b64 exec, exec, s[4:5]
	s_mov_b32 s4, 0xf800000
	v_sqrt_f32_e32 v99, v99
	s_nop 0
.LBB0_395:
	s_or_b64 exec, exec, s[26:27]
	v_add_f32_e32 v81, v5, v81
	v_mul_f32_e32 v81, 0xbfb8aa3b, v81
	v_exp_f32_e32 v81, v81
	s_nop 0
	v_add_f32_e32 v100, 1.0, v81
	v_mov_b32_e32 v81, 1.0
	v_rcp_f32_e32 v100, v100
	s_nop 0
	v_mul_f32_e32 v100, 0xc1000000, v100
	v_mul_f32_e32 v100, v149, v100
	s_and_saveexec_b64 s[26:27], s[24:25]
	s_cbranch_execz .LBB0_401
	v_add_f32_e32 v101, v100, v100
	s_mov_b32 s4, 0xbdcccccd
	v_cmp_nlt_f32_e32 vcc, s4, v101
	s_and_saveexec_b64 s[4:5], vcc
	s_xor_b64 s[4:5], exec, s[4:5]
	v_mul_f32_e32 v81, 0x3fb8aa3b, v101
	v_exp_f32_e32 v81, v81
	s_nop 0
	v_sub_f32_e32 v81, 1.0, v81
	s_andn2_saveexec_b64 s[4:5], s[4:5]
	v_fmamk_f32 v81, v101, 0x3d2aaaab, v171
	v_fma_f32 v81, v101, v81, 0.5
	v_fma_f32 v81, v101, v81, 1.0
	v_mul_f32_e64 v81, v101, -v81
	s_or_b64 exec, exec, s[4:5]
	s_mov_b32 s4, 0xf800000
	v_sqrt_f32_e32 v81, v81
	s_nop 0

.LBB0_402:
	s_or_b64 exec, exec, s[10:11]
	s_nop 0
	v_add_u32_e32 v74, 0x200, v95
	v_ashrrev_i32_e32 v74, 5, v74
	v_add_u32_e32 v84, s48, v74
	s_movk_i32 s4, 0x4080
	v_cmp_gt_i32_e32 vcc, s4, v84
	s_and_saveexec_b64 s[10:11], vcc
	s_cbranch_execz .LBB0_375
	v_ashrrev_i32_e32 v85, 31, v84
	v_lshlrev_b64 v[76:77], 10, v[84:85]
	v_lshl_add_u64 v[76:77], v[140:141], 0, v[76:77]
	global_load_dwordx2 v[82:83], v[76:77], off
	v_mad_u64_u32 v[74:75], s[4:5], v74, s33, v[138:139]
	ds_read_b128 v[78:81], v74
	ds_read_b128 v[74:77], v74 offset:512
	s_movk_i32 s4, 0x3fff
	v_cmp_lt_i32_e32 vcc, s4, v84
	v_and_b32_e32 v95, 0xfff, v84
	s_waitcnt vmcnt(2) lgkmcnt(1)
	v_add_f32_e32 v78, v2, v78
	v_mul_f32_e32 v78, 0xbfb8aa3b, v78
	v_exp_f32_e32 v78, v78
	s_nop 0
	v_add_f32_e32 v78, 1.0, v78
	v_cmp_ne_u32_e64 s[4:5], 0, v95
	s_or_b64 s[24:25], vcc, s[4:5]
	v_mov_b32_e32 v95, 1.0
	v_rcp_f32_e32 v78, v78
	s_nop 0
	v_mul_f32_e32 v78, 0xc1000000, v78
	v_mul_f32_e32 v78, v146, v78
	s_and_saveexec_b64 s[26:27], s[24:25]
	s_cbranch_execz .LBB0_409
	v_add_f32_e32 v96, v78, v78
	s_mov_b32 s4, 0xbdcccccd
	v_cmp_nlt_f32_e32 vcc, s4, v96
	s_and_saveexec_b64 s[4:5], vcc
	s_xor_b64 s[4:5], exec, s[4:5]
	v_mul_f32_e32 v95, 0x3fb8aa3b, v96
	v_exp_f32_e32 v95, v95
	s_nop 0
	v_sub_f32_e32 v95, 1.0, v95
	s_andn2_saveexec_b64 s[4:5], s[4:5]
	v_fmamk_f32 v95, v96, 0x3d2aaaab, v171
	v_fma_f32 v95, v96, v95, 0.5
	v_fma_f32 v95, v96, v95, 1.0
	v_mul_f32_e64 v95, v96, -v95
	s_or_b64 exec, exec, s[4:5]
	s_mov_b32 s4, 0xf800000
	v_sqrt_f32_e32 v95, v95
	s_nop 0
.LBB0_409:
	s_or_b64 exec, exec, s[26:27]
	v_add_f32_e32 v79, v3, v79
	v_mul_f32_e32 v79, 0xbfb8aa3b, v79
	v_exp_f32_e32 v79, v79
	v_lshlrev_b64 v[84:85], 9, v[84:85]
	v_mov_b32_e32 v96, 1.0
	v_add_f32_e32 v79, 1.0, v79
	v_rcp_f32_e32 v79, v79
	s_nop 0
	v_mul_f32_e32 v79, 0xc1000000, v79
	v_mul_f32_e32 v79, v147, v79
	s_and_saveexec_b64 s[26:27], s[24:25]
	s_cbranch_execz .LBB0_415
	v_add_f32_e32 v97, v79, v79
	s_mov_b32 s4, 0xbdcccccd
	v_cmp_nlt_f32_e32 vcc, s4, v97
	s_and_saveexec_b64 s[4:5], vcc
	s_xor_b64 s[4:5], exec, s[4:5]
	v_mul_f32_e32 v96, 0x3fb8aa3b, v97
	v_exp_f32_e32 v96, v96
	s_nop 0
	v_sub_f32_e32 v96, 1.0, v96
	s_andn2_saveexec_b64 s[4:5], s[4:5]
	v_fmamk_f32 v96, v97, 0x3d2aaaab, v171
	v_fma_f32 v96, v97, v96, 0.5
	v_fma_f32 v96, v97, v96, 1.0
	v_mul_f32_e64 v96, v97, -v96
	s_or_b64 exec, exec, s[4:5]
	s_mov_b32 s4, 0xf800000
	v_sqrt_f32_e32 v96, v96
	s_nop 0
.LBB0_415:
	s_or_b64 exec, exec, s[26:27]
	v_add_f32_e32 v80, v4, v80
	v_mul_f32_e32 v80, 0xbfb8aa3b, v80
	v_exp_f32_e32 v80, v80
	v_mov_b32_e32 v97, 1.0
	v_add_f32_e32 v80, 1.0, v80
	v_rcp_f32_e32 v80, v80
	s_nop 0
	v_mul_f32_e32 v80, 0xc1000000, v80
	v_mul_f32_e32 v80, v148, v80
	s_and_saveexec_b64 s[26:27], s[24:25]
	s_cbranch_execz .LBB0_421
	v_add_f32_e32 v99, v80, v80
	s_mov_b32 s4, 0xbdcccccd
	v_cmp_nlt_f32_e32 vcc, s4, v99
	s_and_saveexec_b64 s[4:5], vcc
	s_xor_b64 s[4:5], exec, s[4:5]
	v_mul_f32_e32 v97, 0x3fb8aa3b, v99
	v_exp_f32_e32 v97, v97
	s_nop 0
	v_sub_f32_e32 v97, 1.0, v97
	s_andn2_saveexec_b64 s[4:5], s[4:5]
	v_fmamk_f32 v97, v99, 0x3d2aaaab, v171
	v_fma_f32 v97, v99, v97, 0.5
	v_fma_f32 v97, v99, v97, 1.0
	v_mul_f32_e64 v97, v99, -v97
	s_or_b64 exec, exec, s[4:5]
	s_mov_b32 s4, 0xf800000
	v_sqrt_f32_e32 v97, v97
	s_nop 0

.LBB0_427:
	s_or_b64 exec, exec, s[4:5]
	s_mov_b32 s4, 0xf800000
	v_sqrt_f32_e32 v17, v17
	s_nop 0

.LBB0_430:
	v_add_u32_e32 v0, s49, v139
	v_ashrrev_i32_e32 v10, 5, v0
	v_add_u32_e32 v20, s48, v10
	s_movk_i32 s4, 0x4080
	v_cmp_gt_i32_e32 vcc, s4, v20
	s_and_saveexec_b64 s[10:11], vcc
	s_cbranch_execz .LBB0_456
	v_ashrrev_i32_e32 v21, 31, v20
	v_lshlrev_b64 v[12:13], 10, v[20:21]
	v_lshl_add_u64 v[12:13], v[140:141], 0, v[12:13]
	global_load_dwordx2 v[18:19], v[12:13], off
	v_mad_u64_u32 v[10:11], s[4:5], v10, s33, v[138:139]
	ds_read_b128 v[14:17], v10
	ds_read_b128 v[10:13], v10 offset:512
	s_movk_i32 s4, 0x3fff
	v_cmp_lt_i32_e32 vcc, s4, v20
	v_and_b32_e32 v22, 0xfff, v20
	s_waitcnt vmcnt(2) lgkmcnt(1)
	v_add_f32_e32 v14, v2, v14
	v_mul_f32_e32 v14, 0xbfb8aa3b, v14
	v_exp_f32_e32 v14, v14
	s_nop 0
	v_add_f32_e32 v14, 1.0, v14
	v_cmp_ne_u32_e64 s[4:5], 0, v22
	s_or_b64 s[24:25], vcc, s[4:5]
	v_mov_b32_e32 v22, 1.0
	v_rcp_f32_e32 v14, v14
	s_nop 0
	v_mul_f32_e32 v14, 0xc1000000, v14
	v_mul_f32_e32 v14, v146, v14
	s_and_saveexec_b64 s[26:27], s[24:25]
	s_cbranch_execz .LBB0_437
	v_add_f32_e32 v23, v14, v14
	s_mov_b32 s4, 0xbdcccccd
	v_cmp_nlt_f32_e32 vcc, s4, v23
	s_and_saveexec_b64 s[4:5], vcc
	s_xor_b64 s[4:5], exec, s[4:5]
	v_mul_f32_e32 v22, 0x3fb8aa3b, v23
	v_exp_f32_e32 v22, v22
	s_nop 0
	v_sub_f32_e32 v22, 1.0, v22
	s_andn2_saveexec_b64 s[4:5], s[4:5]
	v_fmamk_f32 v22, v23, 0x3d2aaaab, v171
	v_fma_f32 v22, v23, v22, 0.5
	v_fma_f32 v22, v23, v22, 1.0
	v_mul_f32_e64 v22, v23, -v22
	s_or_b64 exec, exec, s[4:5]
	s_mov_b32 s4, 0xf800000
	v_sqrt_f32_e32 v22, v22
	s_nop 0
.LBB0_437:
	s_or_b64 exec, exec, s[26:27]
	v_add_f32_e32 v15, v3, v15
	v_mul_f32_e32 v15, 0xbfb8aa3b, v15
	v_exp_f32_e32 v15, v15
	v_lshlrev_b64 v[20:21], 9, v[20:21]
	v_mov_b32_e32 v23, 1.0
	v_add_f32_e32 v15, 1.0, v15
	v_rcp_f32_e32 v15, v15
	s_nop 0
	v_mul_f32_e32 v15, 0xc1000000, v15
	v_mul_f32_e32 v15, v147, v15
	s_and_saveexec_b64 s[26:27], s[24:25]
	s_cbranch_execz .LBB0_443
	v_add_f32_e32 v24, v15, v15
	s_mov_b32 s4, 0xbdcccccd
	v_cmp_nlt_f32_e32 vcc, s4, v24
	s_and_saveexec_b64 s[4:5], vcc
	s_xor_b64 s[4:5], exec, s[4:5]
	v_mul_f32_e32 v23, 0x3fb8aa3b, v24
	v_exp_f32_e32 v23, v23
	s_nop 0
	v_sub_f32_e32 v23, 1.0, v23
	s_andn2_saveexec_b64 s[4:5], s[4:5]
	v_fmamk_f32 v23, v24, 0x3d2aaaab, v171
	v_fma_f32 v23, v24, v23, 0.5
	v_fma_f32 v23, v24, v23, 1.0
	v_mul_f32_e64 v23, v24, -v23
	s_or_b64 exec, exec, s[4:5]
	s_mov_b32 s4, 0xf800000
	v_sqrt_f32_e32 v23, v23
	s_nop 0
.LBB0_443:
	s_or_b64 exec, exec, s[26:27]
	v_add_f32_e32 v16, v4, v16
	v_mul_f32_e32 v16, 0xbfb8aa3b, v16
	v_exp_f32_e32 v16, v16
	v_mov_b32_e32 v24, 1.0
	v_add_f32_e32 v16, 1.0, v16
	v_rcp_f32_e32 v16, v16
	s_nop 0
	v_mul_f32_e32 v16, 0xc1000000, v16
	v_mul_f32_e32 v16, v148, v16
	s_and_saveexec_b64 s[26:27], s[24:25]
	s_cbranch_execz .LBB0_449
	v_add_f32_e32 v25, v16, v16
	s_mov_b32 s4, 0xbdcccccd
	v_cmp_nlt_f32_e32 vcc, s4, v25
	s_and_saveexec_b64 s[4:5], vcc
	s_xor_b64 s[4:5], exec, s[4:5]
	v_mul_f32_e32 v24, 0x3fb8aa3b, v25
	v_exp_f32_e32 v24, v24
	s_nop 0
	v_sub_f32_e32 v24, 1.0, v24
	s_andn2_saveexec_b64 s[4:5], s[4:5]
	v_fmamk_f32 v24, v25, 0x3d2aaaab, v171
	v_fma_f32 v24, v25, v24, 0.5
	v_fma_f32 v24, v25, v24, 1.0
	v_mul_f32_e64 v24, v25, -v24
	s_or_b64 exec, exec, s[4:5]
	s_mov_b32 s4, 0xf800000
	v_sqrt_f32_e32 v24, v24
	s_nop 0
.LBB0_449:
	s_or_b64 exec, exec, s[26:27]
	v_add_f32_e32 v17, v5, v17
	v_mul_f32_e32 v17, 0xbfb8aa3b, v17
	v_exp_f32_e32 v17, v17
	s_nop 0
	v_add_f32_e32 v25, 1.0, v17
	v_mov_b32_e32 v17, 1.0
	v_rcp_f32_e32 v25, v25
	s_nop 0
	v_mul_f32_e32 v25, 0xc1000000, v25
	v_mul_f32_e32 v25, v149, v25
	s_and_saveexec_b64 s[26:27], s[24:25]
	s_cbranch_execz .LBB0_455
	v_add_f32_e32 v26, v25, v25
	s_mov_b32 s4, 0xbdcccccd
	v_cmp_nlt_f32_e32 vcc, s4, v26
	s_and_saveexec_b64 s[4:5], vcc
	s_xor_b64 s[4:5], exec, s[4:5]
	v_mul_f32_e32 v17, 0x3fb8aa3b, v26
	v_exp_f32_e32 v17, v17
	s_nop 0
	v_sub_f32_e32 v17, 1.0, v17
	s_andn2_saveexec_b64 s[4:5], s[4:5]
	v_fmamk_f32 v17, v26, 0x3d2aaaab, v171
	v_fma_f32 v17, v26, v17, 0.5
	v_fma_f32 v17, v26, v17, 1.0
	v_mul_f32_e64 v17, v26, -v17
	s_or_b64 exec, exec, s[4:5]
	s_mov_b32 s4, 0xf800000
	v_sqrt_f32_e32 v17, v17
	s_nop 0

.LBB0_456:
	s_or_b64 exec, exec, s[10:11]
	v_add_u32_e32 v0, 0x200, v0
	v_ashrrev_i32_e32 v0, 5, v0
	v_add_u32_e32 v20, s48, v0
	s_movk_i32 s4, 0x4080
	v_cmp_gt_i32_e32 vcc, s4, v20
	s_and_saveexec_b64 s[10:11], vcc
	s_cbranch_execz .LBB0_429
	v_ashrrev_i32_e32 v21, 31, v20
	v_lshlrev_b64 v[10:11], 10, v[20:21]
	v_lshl_add_u64 v[10:11], v[140:141], 0, v[10:11]
	global_load_dwordx2 v[18:19], v[10:11], off
	v_mad_u64_u32 v[10:11], s[4:5], v0, s33, v[138:139]
	ds_read_b128 v[14:17], v10
	ds_read_b128 v[10:13], v10 offset:512
	s_movk_i32 s4, 0x3fff
	v_cmp_lt_i32_e32 vcc, s4, v20
	s_waitcnt vmcnt(2) lgkmcnt(1)
	v_add_f32_e32 v0, v2, v14
	v_mul_f32_e32 v0, 0xbfb8aa3b, v0
	v_exp_f32_e32 v0, v0
	v_and_b32_e32 v14, 0xfff, v20
	v_add_f32_e32 v0, 1.0, v0
	v_cmp_ne_u32_e64 s[4:5], 0, v14
	s_or_b64 s[24:25], vcc, s[4:5]
	v_mov_b32_e32 v14, 1.0
	v_rcp_f32_e32 v0, v0
	s_nop 0
	v_mul_f32_e32 v0, 0xc1000000, v0
	v_mul_f32_e32 v0, v146, v0
	s_and_saveexec_b64 s[26:27], s[24:25]
	s_cbranch_execz .LBB0_463
	v_add_f32_e32 v22, v0, v0
	s_mov_b32 s4, 0xbdcccccd
	v_cmp_nlt_f32_e32 vcc, s4, v22
	s_and_saveexec_b64 s[4:5], vcc
	s_xor_b64 s[4:5], exec, s[4:5]
	v_mul_f32_e32 v14, 0x3fb8aa3b, v22
	v_exp_f32_e32 v14, v14
	s_nop 0
	v_sub_f32_e32 v14, 1.0, v14
	s_andn2_saveexec_b64 s[4:5], s[4:5]
	v_fmamk_f32 v14, v22, 0x3d2aaaab, v171
	v_fma_f32 v14, v22, v14, 0.5
	v_fma_f32 v14, v22, v14, 1.0
	v_mul_f32_e64 v14, v22, -v14
	s_or_b64 exec, exec, s[4:5]
	s_mov_b32 s4, 0xf800000
	v_sqrt_f32_e32 v14, v14
	s_nop 0
.LBB0_463:
	s_or_b64 exec, exec, s[26:27]
	v_add_f32_e32 v15, v3, v15
	v_mul_f32_e32 v15, 0xbfb8aa3b, v15
	v_exp_f32_e32 v15, v15
	v_lshlrev_b64 v[20:21], 9, v[20:21]
	v_mov_b32_e32 v22, 1.0
	v_add_f32_e32 v15, 1.0, v15
	v_rcp_f32_e32 v15, v15
	s_nop 0
	v_mul_f32_e32 v15, 0xc1000000, v15
	v_mul_f32_e32 v15, v147, v15
	s_and_saveexec_b64 s[26:27], s[24:25]
	s_cbranch_execz .LBB0_469
	v_add_f32_e32 v23, v15, v15
	s_mov_b32 s4, 0xbdcccccd
	v_cmp_nlt_f32_e32 vcc, s4, v23
	s_and_saveexec_b64 s[4:5], vcc
	s_xor_b64 s[4:5], exec, s[4:5]
	v_mul_f32_e32 v22, 0x3fb8aa3b, v23
	v_exp_f32_e32 v22, v22
	s_nop 0
	v_sub_f32_e32 v22, 1.0, v22
	s_andn2_saveexec_b64 s[4:5], s[4:5]
	v_fmamk_f32 v22, v23, 0x3d2aaaab, v171
	v_fma_f32 v22, v23, v22, 0.5
	v_fma_f32 v22, v23, v22, 1.0
	v_mul_f32_e64 v22, v23, -v22
	s_or_b64 exec, exec, s[4:5]
	s_mov_b32 s4, 0xf800000
	v_sqrt_f32_e32 v22, v22
	s_nop 0
.LBB0_469:
	s_or_b64 exec, exec, s[26:27]
	v_add_f32_e32 v16, v4, v16
	v_mul_f32_e32 v16, 0xbfb8aa3b, v16
	v_exp_f32_e32 v16, v16
	v_mov_b32_e32 v23, 1.0
	v_add_f32_e32 v16, 1.0, v16
	v_rcp_f32_e32 v16, v16
	s_nop 0
	v_mul_f32_e32 v16, 0xc1000000, v16
	v_mul_f32_e32 v16, v148, v16
	s_and_saveexec_b64 s[26:27], s[24:25]
	s_cbranch_execz .LBB0_475
	v_add_f32_e32 v24, v16, v16
	s_mov_b32 s4, 0xbdcccccd
	v_cmp_nlt_f32_e32 vcc, s4, v24
	s_and_saveexec_b64 s[4:5], vcc
	s_xor_b64 s[4:5], exec, s[4:5]
	v_mul_f32_e32 v23, 0x3fb8aa3b, v24
	v_exp_f32_e32 v23, v23
	s_nop 0
	v_sub_f32_e32 v23, 1.0, v23
	s_andn2_saveexec_b64 s[4:5], s[4:5]
	v_fmamk_f32 v23, v24, 0x3d2aaaab, v171
	v_fma_f32 v23, v24, v23, 0.5
	v_fma_f32 v23, v24, v23, 1.0
	v_mul_f32_e64 v23, v24, -v23
	s_or_b64 exec, exec, s[4:5]
	s_mov_b32 s4, 0xf800000
	v_sqrt_f32_e32 v23, v23
	s_nop 0
